# split-K unit preambles after a tile loop: vestigial counted vmcnt waits (guards for registers the tile epilogue loaded) dropped, so the tile's last stores drain behind the unit's DMAs
# speedup vs baseline: 1.0065x; 1.0005x over previous
; #define LAS __attribute__((address_space(3)))
; __device__ __forceinline__ int opq(int v) { asm volatile("" : "+v"(v)); return v; }
; template <int CT, class Epi> __device__ __forceinline__ void skinny_gemm(LAS unsigned char* lds, const bf16_t* A, const bf16_t* Bt, int N, int K, const Epi& E, int first) {
;     const int tid = opq(threadIdx.x), lane = tid & 63, wave = __builtin_amdgcn_readfirstlane(tid >> 6), r = lane & 15, qd = lane >> 4;
;     const int G = gridDim.x, nunits = 8 * (N / (16 * CT)), kw = K / 8, nsteps = kw / 32;
;     LAS float* red = (LAS float*)lds;
;     for (int u = (int)((blockIdx.x + G - first % G) % G); u < nunits; u += G) {
;         const int mt = u & 7, nt = u >> 3;
;         const bf16_t* ap = A + (size_t)(NTOK_P + mt * 64 + r) * K + wave * kw + 8 * qd;
;         const bf16_t* bp = Bt + (size_t)(nt * 16 * CT + r) * K + wave * kw + 8 * qd;
.LBB0_265:
	v_readlane_b32 s0, v254, 55
	v_mov_b32_e32 v20, v184
	v_readlane_b32 s1, v254, 56
	s_andn2_b64 vcc, exec, s[0:1]
	v_readfirstlane_b32 s0, v20
	s_cbranch_vccnz .LBB0_276
	s_ashr_i32 s6, s0, 6
	v_ashrrev_i32_e32 v22, 31, v20
	s_lshl_b32 s0, s6, 7
	v_lshrrev_b32_e32 v22, 28, v22
	s_ashr_i32 s1, s0, 31
	v_add_u32_e32 v22, v20, v22
	s_lshl_b64 s[0:1], s[0:1], 1
	v_ashrrev_i32_e32 v43, 4, v22
	v_and_b32_e32 v22, -16, v22
	v_and_b32_e32 v42, 15, v20
	s_add_u32 s4, s30, s0
	v_and_b32_e32 v0, 48, v20
	v_sub_u32_e32 v22, v20, v22
	v_add_u32_e32 v20, 0x200, v20
	s_addc_u32 s5, s31, s1
	v_ashrrev_i32_e32 v23, 31, v20
	v_lshl_add_u64 v[2:3], s[4:5], 0, v[0:1]
	v_readlane_b32 s4, v255, 37
	v_lshrrev_b32_e32 v23, 28, v23
	s_add_u32 s0, s4, s0
	v_readlane_b32 s4, v255, 38
	v_add_u32_e32 v23, v20, v23
	s_addc_u32 s1, s4, s1
	v_ashrrev_i32_e32 v45, 4, v23
	v_and_b32_e32 v23, -16, v23
	s_nop 0
	v_lshl_add_u64 v[28:29], s[0:1], 0, v[0:1]
	s_lshl_b32 s0, s6, 14
	v_lshlrev_b32_e32 v44, 2, v22
	v_sub_u32_e32 v20, v20, v23
	v_lshlrev_b32_e32 v23, 8, v43
	v_lshlrev_b32_e32 v22, 4, v22
	s_add_i32 s0, s0, 0
	v_lshlrev_b32_e32 v46, 2, v20
	v_add3_u32 v47, 0, v23, v22
	v_lshlrev_b32_e32 v22, 8, v45
	v_lshlrev_b32_e32 v20, 4, v20
	v_lshl_add_u32 v21, v42, 8, s0
	v_add3_u32 v52, 0, v22, v20
	v_add_u32_e32 v48, 0x10000, v47
	v_add_u32_e32 v49, 0x14000, v47
	v_add_u32_e32 v50, 0x18000, v47
	v_add_u32_e32 v51, 0x1c000, v47
	v_add_u32_e32 v53, 0x10000, v52
	v_add_u32_e32 v54, 0x14000, v52
	v_add_u32_e32 v55, 0x18000, v52
	v_add_u32_e32 v56, 0x1c000, v52
	v_add_u32_e32 v57, v21, v0
	v_readlane_b32 s8, v255, 11
	v_readlane_b32 s9, v255, 10
	v_readlane_b32 s10, v255, 17
	s_branch .LBB0_268

;     __device__ __forceinline__ void prefetch4(int row, int col, Pre& p) const { p.gw = *(const u32x2*)(Zg + (size_t)row * INC + col); if (SECOND) p.pw = *(const u32x2*)(O + (size_t)row * DM + col); }
; template <int CT, class Epi> __device__ __forceinline__ void skinny_gemm(LAS unsigned char* lds, const bf16_t* A, const bf16_t* Bt, int N, int K, const Epi& E, int first) {
;     ...
;     for (int u = (int)((blockIdx.x + G - first % G) % G); u < nunits; u += G) {
;         const int mt = u & 7, nt = u >> 3;
;         const bf16_t* ap = A + (size_t)(NTOK_P + mt * 64 + r) * K + wave * kw + 8 * qd;
;         const bf16_t* bp = Bt + (size_t)(nt * 16 * CT + r) * K + wave * kw + 8 * qd;
;         typename Epi::Pre pre[CT / 2];
; #pragma unroll
;         for (int e = 0; e < CT / 2; ++e) { const int idx = tid + e * 512; E.prefetch4(NTOK_P + mt * 64 + idx / (4 * CT), nt * 16 * CT + (idx % (4 * CT)) * 4, pre[e]); }
;         f32x4 acc[4][CT];
; #pragma unroll
;         for (int rt = 0; rt < 4; ++rt)
; #pragma unroll
;             for (int ct = 0; ct < CT; ++ct) acc[rt][ct] = (f32x4){0.f, 0.f, 0.f, 0.f};
.LBB0_590:
	s_and_b32 s7, s0, 0x1c0
	s_bitset1_b32 s7, 14
	v_or_b32_e32 v0, s7, v22
	v_lshlrev_b32_e32 v0, 10, v0
	s_and_b32 s10, s1, 0xffffffe0
	v_lshl_add_u64 v[36:37], v[2:3], 0, v[0:1]
	v_or_b32_e32 v28, s10, v22
	v_add_co_u32_e32 v44, vcc, s84, v36
	v_ashrrev_i32_e32 v29, 31, v28
	s_nop 0
	v_addc_co_u32_e32 v45, vcc, 0, v37, vcc
	v_lshlrev_b64 v[32:33], 10, v[28:29]
	v_add_u32_e32 v28, s7, v23
	v_add_co_u32_e32 v52, vcc, s85, v36
	s_and_b32 s7, s6, 0x3ffffff8
	v_ashrrev_i32_e32 v29, 31, v28
	v_addc_co_u32_e32 v53, vcc, 0, v37, vcc
	v_add_lshl_u32 v30, s7, v24, 2
	v_lshlrev_b64 v[92:93], 10, v[28:29]
	v_add_co_u32_e32 v60, vcc, s72, v36
	v_lshl_add_u64 v[28:29], s[40:41], 0, v[92:93]
	v_ashrrev_i32_e32 v31, 31, v30
	s_nop 0
	v_lshl_add_u64 v[68:69], v[20:21], 0, v[32:33]
	v_addc_co_u32_e32 v61, vcc, 0, v37, vcc
	v_lshl_add_u64 v[28:29], v[30:31], 1, v[28:29]
	v_add_co_u32_e32 v76, vcc, s84, v68
	global_load_dwordx2 v[94:95], v[28:29], off
	v_lshl_add_u64 v[28:29], v[30:31], 2, s[8:9]
	v_addc_co_u32_e32 v77, vcc, 0, v69, vcc
	global_load_dwordx4 v[28:31], v[28:29], off
	s_nop 0
	s_mov_b32 s100, 0x2000
	s_mov_b32 s101, 0
	v_readfirstlane_b32 s98, v184
	v_and_b32_e32 v246, 63, v184
	s_nop 1
	s_lshr_b32 s98, s98, 6
	s_lshl_b32 s99, s98, 12
	s_add_i32 s99, s99, 0x10000
	s_lshl_b32 s98, s98, 13
	v_and_b32_e32 v247, 15, v246
	v_lshrrev_b32_e32 v248, 4, v246
	v_lshrrev_b32_e32 v249, 3, v246
	v_and_b32_e32 v246, 7, v246
	v_xor_b32_e32 v246, v246, v249
	v_sub_u32_e32 v249, v249, v247
	v_sub_u32_e32 v246, v246, v248
	v_lshlrev_b32_e32 v249, 10, v249
	v_lshl_add_u32 v240, v246, 4, v249
	v_ashrrev_i32_e32 v241, 31, v240
	v_and_b32_e32 v246, 7, v247
	v_xor_b32_e32 v246, v246, v248
	v_lshlrev_b32_e32 v246, 4, v246
	v_lshl_add_u32 v246, v247, 7, v246
	v_add_u32_e32 v242, s98, v246
	v_xor_b32_e32 v243, 64, v242
	v_add_u32_e32 v244, s99, v246
	v_xor_b32_e32 v245, 64, v244
	s_mov_b32 m0, s98
	v_lshl_add_u64 v[236:237], v[36:37], 0, v[240:241]
	global_load_lds_dwordx4 v[236:237], off
	s_add_i32 m0, s98, 0x400
	v_lshl_add_u64 v[236:237], v[236:237], 0, s[100:101]
	global_load_lds_dwordx4 v[236:237], off
	s_add_i32 m0, s98, 0x800
	v_lshl_add_u64 v[236:237], v[236:237], 0, s[100:101]
	global_load_lds_dwordx4 v[236:237], off
	s_add_i32 m0, s98, 0xc00
	v_lshl_add_u64 v[236:237], v[236:237], 0, s[100:101]
	global_load_lds_dwordx4 v[236:237], off
	s_add_i32 m0, s98, 0x1000
	v_lshl_add_u64 v[236:237], v[236:237], 0, s[100:101]
	global_load_lds_dwordx4 v[236:237], off
	s_add_i32 m0, s98, 0x1400
	v_lshl_add_u64 v[236:237], v[236:237], 0, s[100:101]
	global_load_lds_dwordx4 v[236:237], off
	s_add_i32 m0, s98, 0x1800
	v_lshl_add_u64 v[236:237], v[236:237], 0, s[100:101]
	global_load_lds_dwordx4 v[236:237], off
	s_add_i32 m0, s98, 0x1c00
	v_lshl_add_u64 v[236:237], v[236:237], 0, s[100:101]
	global_load_lds_dwordx4 v[236:237], off
	s_mov_b32 m0, s99
	v_lshl_add_u64 v[238:239], v[68:69], 0, v[240:241]
	global_load_lds_dwordx4 v[238:239], off
	s_add_i32 m0, s99, 0x400
	v_lshl_add_u64 v[238:239], v[238:239], 0, s[100:101]
	global_load_lds_dwordx4 v[238:239], off
	s_add_i32 m0, s99, 0x800
	v_lshl_add_u64 v[238:239], v[238:239], 0, s[100:101]
	global_load_lds_dwordx4 v[238:239], off
	s_add_i32 m0, s99, 0xc00
	v_lshl_add_u64 v[238:239], v[238:239], 0, s[100:101]
	global_load_lds_dwordx4 v[238:239], off
	s_waitcnt vmcnt(0)
	ds_read_b128 v[32:35], v242
	ds_read_b128 v[40:43], v242 offset:2048
	ds_read_b128 v[48:51], v242 offset:4096
	ds_read_b128 v[56:59], v242 offset:6144
	ds_read_b128 v[36:39], v243
	ds_read_b128 v[44:47], v243 offset:2048
	ds_read_b128 v[52:55], v243 offset:4096
	ds_read_b128 v[60:63], v243 offset:6144
	ds_read_b128 v[64:67], v244
	ds_read_b128 v[72:75], v244 offset:2048
	ds_read_b128 v[68:71], v245
	ds_read_b128 v[76:79], v245 offset:2048
	s_waitcnt lgkmcnt(0)
	s_nop 0
	s_nop 0
	s_nop 0
	s_nop 0
	s_nop 0
	s_nop 0
	s_nop 0
	s_nop 0
	s_nop 0
	s_nop 0
	s_nop 0
	v_readlane_b32 s99, v254, 11
	v_readlane_b32 s98, v254, 10
	s_cmp_lt_i32 s99, 1
	s_cbranch_scc1 .Lsp_skip
	s_and_b32 s98, s98, 0xff
	v_readlane_b32 s101, v255, 41
	s_lshr_b32 s100, s98, 1
	s_and_b32 s98, s98, 1
	s_lshl_b32 s101, s101, 7
	s_add_i32 s100, s100, s101
	s_lshl_b32 s98, s98, 8
	s_lshl_b32 s100, s100, 16
	s_add_i32 s100, s100, s98
	v_and_b32_e32 v116, 0xff, v184
	v_lshrrev_b32_e32 v117, 1, v116
	v_and_b32_e32 v116, 1, v116
	v_lshlrev_b32_e32 v117, 9, v117
	v_lshl_add_u32 v116, v116, 7, v117
	v_add_u32_e32 v116, s100, v116
	v_mov_b32_e32 v117, 0
	v_mov_b32_e32 v118, s54
	v_mov_b32_e32 v119, s55
	v_mov_b32_e32 v120, s52
	v_mov_b32_e32 v121, s53
	v_cmp_gt_u32_e32 vcc, 0x100, v184
	v_cndmask_b32_e32 v118, v118, v120, vcc
	v_cndmask_b32_e32 v119, v119, v121, vcc
	v_lshl_add_u64 v[118:119], v[118:119], 0, v[116:117]
	global_load_dword v116, v[118:119], off

; #define LAS __attribute__((address_space(3)))
;     __device__ __forceinline__ void prefetch4(int row, int col, Pre& p) const { p.gw = *(const u32x2*)(Zg + (size_t)row * INC + col); if (SECOND) p.pw = *(const u32x2*)(O + (size_t)row * DM + col); }
; template <int CT, class Epi> __device__ __forceinline__ void skinny_gemm(LAS unsigned char* lds, const bf16_t* A, const bf16_t* Bt, int N, int K, const Epi& E, int first) {
;     ...
;     for (int u = (int)((blockIdx.x + G - first % G) % G); u < nunits; u += G) {
;         const int mt = u & 7, nt = u >> 3;
;         const bf16_t* ap = A + (size_t)(NTOK_P + mt * 64 + r) * K + wave * kw + 8 * qd;
;         const bf16_t* bp = Bt + (size_t)(nt * 16 * CT + r) * K + wave * kw + 8 * qd;
;         typename Epi::Pre pre[CT / 2];
; #pragma unroll
;         for (int e = 0; e < CT / 2; ++e) { const int idx = tid + e * 512; E.prefetch4(NTOK_P + mt * 64 + idx / (4 * CT), nt * 16 * CT + (idx % (4 * CT)) * 4, pre[e]); }
;         f32x4 acc[4][CT];
; #pragma unroll
;         for (int rt = 0; rt < 4; ++rt)
; #pragma unroll
;             for (int ct = 0; ct < CT; ++ct) acc[rt][ct] = (f32x4){0.f, 0.f, 0.f, 0.f};
;     ...
;         if (nsteps >= 4) {
; #pragma unroll 1
;             for (int s0 = 0; s0 < nsteps; s0 += 4) SKINNY_GROUP(4, s0);
;         } else SKINNY_GROUP(2, 0);
;     ...
; #pragma unroll
;         for (int rt = 0; rt < 4; ++rt)
; #pragma unroll
;             for (int ct = 0; ct < CT; ++ct) *(LAS f32x4*)(red + wave * (64 * 16 * CT) + (rt * 16 + r) * (16 * CT) + ct * 16 + 4 * qd) = acc[rt][ct];
;         __syncthreads();
; #pragma unroll
;         for (int e = 0; e < CT / 2; ++e) { const int idx = tid + e * 512, row = idx / (4 * CT), c4 = idx % (4 * CT);
;             f32x4 v = *(const LAS f32x4*)(red + row * (16 * CT) + c4 * 4);
; #pragma unroll
;             for (int w = 1; w < 8; ++w) v = v + *(const LAS f32x4*)(red + w * (64 * 16 * CT) + row * (16 * CT) + c4 * 4);
;             E.apply4(NTOK_P + mt * 64 + row, nt * 16 * CT + c4 * 4, v, pre[e]); }
;         __syncthreads();
.LBB0_685:
	s_and_b32 s5, s0, 0x1c0
	s_bitset1_b32 s5, 14
	v_or_b32_e32 v0, s5, v22
	v_lshlrev_b32_e32 v0, 10, v0
	v_lshl_add_u64 v[36:37], v[2:3], 0, v[0:1]
	s_nop 0
	v_add_co_u32_e32 v64, vcc, s84, v36
	s_and_b32 s8, s1, 0xffffffe0
	s_nop 0
	v_addc_co_u32_e32 v65, vcc, 0, v37, vcc
	v_or_b32_e32 v28, s8, v22
	v_add_co_u32_e32 v52, vcc, s85, v36
	v_ashrrev_i32_e32 v29, 31, v28
	s_nop 0
	v_addc_co_u32_e32 v53, vcc, 0, v37, vcc
	v_lshlrev_b64 v[28:29], 10, v[28:29]
	v_add_u32_e32 v88, s5, v23
	s_and_b32 s5, s4, 0x3ffffff8
	v_add_co_u32_e32 v60, vcc, s72, v36
	v_add_lshl_u32 v30, s5, v24, 2
	v_mov_b64_e32 v[32:33], s[10:11]
	s_nop 0
	v_lshl_add_u64 v[68:69], v[20:21], 0, v[28:29]
	v_addc_co_u32_e32 v61, vcc, 0, v37, vcc
	v_mad_i64_i32 v[32:33], s[6:7], v88, s87, v[32:33]
	v_ashrrev_i32_e32 v31, 31, v30
	s_nop 0
	v_add_co_u32_e32 v72, vcc, s84, v68
	v_lshl_add_u64 v[30:31], v[30:31], 1, v[32:33]
	s_nop 0
	v_addc_co_u32_e32 v73, vcc, 0, v69, vcc
	global_load_dwordx2 v[90:91], v[30:31], off
	s_nop 0
	s_mov_b32 s100, 0x2000
	s_mov_b32 s101, 0
	v_readfirstlane_b32 s98, v184
	v_and_b32_e32 v246, 63, v184
	s_nop 1
	s_lshr_b32 s98, s98, 6
	s_lshl_b32 s99, s98, 12
	s_add_i32 s99, s99, 0x10000
	s_lshl_b32 s98, s98, 13
	v_and_b32_e32 v247, 15, v246
	v_lshrrev_b32_e32 v248, 4, v246
	v_lshrrev_b32_e32 v249, 3, v246
	v_and_b32_e32 v246, 7, v246
	v_xor_b32_e32 v246, v246, v249
	v_sub_u32_e32 v249, v249, v247
	v_sub_u32_e32 v246, v246, v248
	v_lshlrev_b32_e32 v249, 10, v249
	v_lshl_add_u32 v240, v246, 4, v249
	v_ashrrev_i32_e32 v241, 31, v240
	v_and_b32_e32 v246, 7, v247
	v_xor_b32_e32 v246, v246, v248
	v_lshlrev_b32_e32 v246, 4, v246
	v_lshl_add_u32 v246, v247, 7, v246
	v_add_u32_e32 v242, s98, v246
	v_xor_b32_e32 v243, 64, v242
	v_add_u32_e32 v244, s99, v246
	v_xor_b32_e32 v245, 64, v244
	s_mov_b32 m0, s98
	v_lshl_add_u64 v[236:237], v[36:37], 0, v[240:241]
	global_load_lds_dwordx4 v[236:237], off
	s_add_i32 m0, s98, 0x400
	v_lshl_add_u64 v[236:237], v[236:237], 0, s[100:101]
	global_load_lds_dwordx4 v[236:237], off
	s_add_i32 m0, s98, 0x800
	v_lshl_add_u64 v[236:237], v[236:237], 0, s[100:101]
	global_load_lds_dwordx4 v[236:237], off
	s_add_i32 m0, s98, 0xc00
	v_lshl_add_u64 v[236:237], v[236:237], 0, s[100:101]
	global_load_lds_dwordx4 v[236:237], off
	s_add_i32 m0, s98, 0x1000
	v_lshl_add_u64 v[236:237], v[236:237], 0, s[100:101]
	global_load_lds_dwordx4 v[236:237], off
	s_add_i32 m0, s98, 0x1400
	v_lshl_add_u64 v[236:237], v[236:237], 0, s[100:101]
	global_load_lds_dwordx4 v[236:237], off
	s_add_i32 m0, s98, 0x1800
	v_lshl_add_u64 v[236:237], v[236:237], 0, s[100:101]
	global_load_lds_dwordx4 v[236:237], off
	s_add_i32 m0, s98, 0x1c00
	v_lshl_add_u64 v[236:237], v[236:237], 0, s[100:101]
	global_load_lds_dwordx4 v[236:237], off
	s_mov_b32 m0, s99
	v_lshl_add_u64 v[238:239], v[68:69], 0, v[240:241]
	global_load_lds_dwordx4 v[238:239], off
	s_add_i32 m0, s99, 0x400
	v_lshl_add_u64 v[238:239], v[238:239], 0, s[100:101]
	global_load_lds_dwordx4 v[238:239], off
	s_add_i32 m0, s99, 0x800
	v_lshl_add_u64 v[238:239], v[238:239], 0, s[100:101]
	global_load_lds_dwordx4 v[238:239], off
	s_add_i32 m0, s99, 0xc00
	v_lshl_add_u64 v[238:239], v[238:239], 0, s[100:101]
	global_load_lds_dwordx4 v[238:239], off
	s_waitcnt vmcnt(0)
	ds_read_b128 v[28:31], v242
	ds_read_b128 v[64:67], v242 offset:2048
	ds_read_b128 v[40:43], v242 offset:4096
	ds_read_b128 v[48:51], v242 offset:6144
	ds_read_b128 v[36:39], v243
	ds_read_b128 v[44:47], v243 offset:2048
	ds_read_b128 v[52:55], v243 offset:4096
	ds_read_b128 v[60:63], v243 offset:6144
	ds_read_b128 v[32:35], v244
	ds_read_b128 v[56:59], v244 offset:2048
	ds_read_b128 v[68:71], v245
	ds_read_b128 v[72:75], v245 offset:2048
	s_waitcnt lgkmcnt(0)
	s_nop 0
	s_nop 0
	s_nop 0
	s_nop 0
	s_nop 0
	s_nop 0
	s_nop 0
	s_nop 0
	v_ashrrev_i32_e32 v89, 31, v88
	v_mfma_f32_16x16x32_bf16 v[76:79], v[32:35], v[28:31], 0
	v_mfma_f32_16x16x32_bf16 v[28:31], v[56:59], v[28:31], 0
	v_mfma_f32_16x16x32_bf16 v[80:83], v[32:35], v[64:67], 0
	v_mfma_f32_16x16x32_bf16 v[64:67], v[56:59], v[64:67], 0
	v_mfma_f32_16x16x32_bf16 v[84:87], v[32:35], v[40:43], 0
	v_mfma_f32_16x16x32_bf16 v[40:43], v[56:59], v[40:43], 0
	v_mfma_f32_16x16x32_bf16 v[32:35], v[32:35], v[48:51], 0
	v_mfma_f32_16x16x32_bf16 v[48:51], v[56:59], v[48:51], 0
	v_mfma_f32_16x16x32_bf16 v[56:59], v[68:71], v[36:39], v[76:79]
	v_mfma_f32_16x16x32_bf16 v[28:31], v[72:75], v[36:39], v[28:31]
	v_mfma_f32_16x16x32_bf16 v[36:39], v[68:71], v[44:47], v[80:83]
	v_mfma_f32_16x16x32_bf16 v[44:47], v[72:75], v[44:47], v[64:67]
	v_mfma_f32_16x16x32_bf16 v[64:67], v[68:71], v[52:55], v[84:87]
	v_mfma_f32_16x16x32_bf16 v[40:43], v[72:75], v[52:55], v[40:43]
	v_mfma_f32_16x16x32_bf16 v[32:35], v[68:71], v[60:63], v[32:35]
	v_mfma_f32_16x16x32_bf16 v[48:51], v[72:75], v[60:63], v[48:51]
	ds_write_b128 v27, v[56:59]
	s_nop 0
	ds_write_b128 v27, v[28:31] offset:64
	ds_write_b128 v27, v[36:39] offset:2048
	ds_write_b128 v27, v[44:47] offset:2112
	ds_write_b128 v27, v[64:67] offset:4096
	ds_write_b128 v27, v[40:43] offset:4160
	ds_write_b128 v27, v[32:35] offset:6144
	ds_write_b128 v27, v[48:51] offset:6208
	s_waitcnt lgkmcnt(0)
	s_barrier
	ds_read_b128 v[28:31], v26
	ds_read_b128 v[32:35], v26 offset:8192
	ds_read_b128 v[36:39], v26 offset:16384
	ds_read_b128 v[40:43], v26 offset:24576
	v_add_u32_e32 v44, s8, v25
	v_lshlrev_b64 v[46:47], 11, v[88:89]
	s_waitcnt lgkmcnt(2)
	v_pk_add_f32 v[30:31], v[30:31], v[34:35]
	v_pk_add_f32 v[32:33], v[28:29], v[32:33]
	s_waitcnt lgkmcnt(1)
	v_pk_add_f32 v[34:35], v[30:31], v[38:39]
	ds_read_b128 v[28:31], v26 offset:32768
	v_pk_add_f32 v[32:33], v[32:33], v[36:37]
	s_waitcnt lgkmcnt(1)
	v_pk_add_f32 v[36:37], v[34:35], v[42:43]
	v_pk_add_f32 v[40:41], v[32:33], v[40:41]
	ds_read_b128 v[32:35], v26 offset:40960
	s_waitcnt lgkmcnt(1)
	v_pk_add_f32 v[42:43], v[36:37], v[30:31]
	ds_read_b128 v[36:39], v26 offset:49152
	v_pk_add_f32 v[40:41], v[40:41], v[28:29]
	ds_read_b128 v[28:31], v26 offset:57344
	s_waitcnt lgkmcnt(2)
	v_pk_add_f32 v[34:35], v[42:43], v[34:35]
	v_pk_add_f32 v[32:33], v[40:41], v[32:33]
	s_waitcnt lgkmcnt(1)
	v_pk_add_f32 v[34:35], v[34:35], v[38:39]
	v_pk_add_f32 v[32:33], v[32:33], v[36:37]
	v_ashrrev_i32_e32 v45, 31, v44
	v_lshlrev_b32_e32 v0, 16, v90
	v_and_b32_e32 v48, 0xffff0000, v90
	v_lshlrev_b32_e32 v49, 16, v91
	s_waitcnt lgkmcnt(0)
	v_pk_add_f32 v[30:31], v[34:35], v[30:31]
	v_pk_add_f32 v[28:29], v[32:33], v[28:29]
	v_lshl_add_u64 v[32:33], s[68:69], 0, v[46:47]
	s_add_i32 s4, s4, s34
	s_add_i32 s1, s1, s83
	s_add_i32 s0, s0, s82
	v_and_b32_e32 v50, 0xffff0000, v91
	v_lshl_add_u64 v[32:33], v[44:45], 1, v[32:33]
	v_mul_f32_e32 v0, v28, v0
	v_mul_f32_e32 v28, v29, v48
	v_mul_f32_e32 v29, v30, v49
	s_cmpk_lt_i32 s4, 0x100
	v_mul_f32_e32 v30, v31, v50
	v_cvt_pk_bf16_f32 v28, v0, v28
	v_cvt_pk_bf16_f32 v29, v29, v30
	global_store_dwordx2 v[32:33], v[28:29], off
	s_barrier
	s_cbranch_scc1 .LBB0_685

;     __device__ __forceinline__ void prefetch4(int row, int col, Pre& p) const { p.gw = *(const u32x2*)(Zg + (size_t)row * INC + col); if (SECOND) p.pw = *(const u32x2*)(O + (size_t)row * DM + col); }
; template <int CT, class Epi> __device__ __forceinline__ void skinny_gemm(LAS unsigned char* lds, const bf16_t* A, const bf16_t* Bt, int N, int K, const Epi& E, int first) {
;     ...
;     for (int u = (int)((blockIdx.x + G - first % G) % G); u < nunits; u += G) {
;         const int mt = u & 7, nt = u >> 3;
;         const bf16_t* ap = A + (size_t)(NTOK_P + mt * 64 + r) * K + wave * kw + 8 * qd;
;         const bf16_t* bp = Bt + (size_t)(nt * 16 * CT + r) * K + wave * kw + 8 * qd;
;         typename Epi::Pre pre[CT / 2];
; #pragma unroll
;         for (int e = 0; e < CT / 2; ++e) { const int idx = tid + e * 512; E.prefetch4(NTOK_P + mt * 64 + idx / (4 * CT), nt * 16 * CT + (idx % (4 * CT)) * 4, pre[e]); }
;         f32x4 acc[4][CT];
; #pragma unroll
;         for (int rt = 0; rt < 4; ++rt)
; #pragma unroll
;             for (int ct = 0; ct < CT; ++ct) acc[rt][ct] = (f32x4){0.f, 0.f, 0.f, 0.f};
.LBB0_708:
	s_and_b32 s5, s0, 0x1c0
	s_bitset1_b32 s5, 14
	v_or_b32_e32 v0, s5, v22
	v_add_u32_e32 v30, s5, v23
	s_and_b32 s5, s4, 0x3ffffff8
	v_add_lshl_u32 v32, s5, v24, 2
	v_ashrrev_i32_e32 v31, 31, v30
	v_mov_b64_e32 v[34:35], s[10:11]
	v_mad_i64_i32 v[34:35], s[6:7], v30, s87, v[34:35]
	v_ashrrev_i32_e32 v33, 31, v32
	v_lshlrev_b64 v[30:31], 11, v[30:31]
	v_lshlrev_b64 v[32:33], 1, v[32:33]
	s_nop 0
	v_lshl_add_u64 v[90:91], s[68:69], 0, v[30:31]
	v_lshlrev_b32_e32 v0, 10, v0
	v_lshl_add_u64 v[34:35], v[34:35], 0, v[32:33]
	v_lshl_add_u64 v[30:31], v[90:91], 0, v[32:33]
	v_lshl_add_u64 v[32:33], v[2:3], 0, v[0:1]
	v_add_co_u32_e32 v40, vcc, s84, v32
	s_and_b32 s8, s1, 0xffffffe0
	s_nop 0
	v_addc_co_u32_e32 v41, vcc, 0, v33, vcc
	v_or_b32_e32 v28, s8, v22
	v_add_co_u32_e32 v48, vcc, s85, v32
	v_ashrrev_i32_e32 v29, 31, v28
	s_nop 0
	v_addc_co_u32_e32 v49, vcc, 0, v33, vcc
	v_lshlrev_b64 v[28:29], 10, v[28:29]
	v_add_co_u32_e32 v56, vcc, s72, v32
	v_lshl_add_u64 v[64:65], v[20:21], 0, v[28:29]
	s_nop 0
	v_addc_co_u32_e32 v57, vcc, 0, v33, vcc
	v_add_co_u32_e32 v72, vcc, s84, v64
	global_load_dwordx2 v[88:89], v[34:35], off
	s_nop 0
	v_addc_co_u32_e32 v73, vcc, 0, v65, vcc
	global_load_dwordx2 v[92:93], v[30:31], off
	s_nop 0
	s_mov_b32 s100, 0x2000
	s_mov_b32 s101, 0
	v_readfirstlane_b32 s98, v184
	v_and_b32_e32 v246, 63, v184
	s_nop 1
	s_lshr_b32 s98, s98, 6
	s_lshl_b32 s99, s98, 12
	s_add_i32 s99, s99, 0x10000
	s_lshl_b32 s98, s98, 13
	v_and_b32_e32 v247, 15, v246
	v_lshrrev_b32_e32 v248, 4, v246
	v_lshrrev_b32_e32 v249, 3, v246
	v_and_b32_e32 v246, 7, v246
	v_xor_b32_e32 v246, v246, v249
	v_sub_u32_e32 v249, v249, v247
	v_sub_u32_e32 v246, v246, v248
	v_lshlrev_b32_e32 v249, 10, v249
	v_lshl_add_u32 v240, v246, 4, v249
	v_ashrrev_i32_e32 v241, 31, v240
	v_and_b32_e32 v246, 7, v247
	v_xor_b32_e32 v246, v246, v248
	v_lshlrev_b32_e32 v246, 4, v246
	v_lshl_add_u32 v246, v247, 7, v246
	v_add_u32_e32 v242, s98, v246
	v_xor_b32_e32 v243, 64, v242
	v_add_u32_e32 v244, s99, v246
	v_xor_b32_e32 v245, 64, v244
	s_mov_b32 m0, s98
	v_lshl_add_u64 v[236:237], v[32:33], 0, v[240:241]
	global_load_lds_dwordx4 v[236:237], off
	s_add_i32 m0, s98, 0x400
	v_lshl_add_u64 v[236:237], v[236:237], 0, s[100:101]
	global_load_lds_dwordx4 v[236:237], off
	s_add_i32 m0, s98, 0x800
	v_lshl_add_u64 v[236:237], v[236:237], 0, s[100:101]
	global_load_lds_dwordx4 v[236:237], off
	s_add_i32 m0, s98, 0xc00
	v_lshl_add_u64 v[236:237], v[236:237], 0, s[100:101]
	global_load_lds_dwordx4 v[236:237], off
	s_add_i32 m0, s98, 0x1000
	v_lshl_add_u64 v[236:237], v[236:237], 0, s[100:101]
	global_load_lds_dwordx4 v[236:237], off
	s_add_i32 m0, s98, 0x1400
	v_lshl_add_u64 v[236:237], v[236:237], 0, s[100:101]
	global_load_lds_dwordx4 v[236:237], off
	s_add_i32 m0, s98, 0x1800
	v_lshl_add_u64 v[236:237], v[236:237], 0, s[100:101]
	global_load_lds_dwordx4 v[236:237], off
	s_add_i32 m0, s98, 0x1c00
	v_lshl_add_u64 v[236:237], v[236:237], 0, s[100:101]
	global_load_lds_dwordx4 v[236:237], off
	s_mov_b32 m0, s99
	v_lshl_add_u64 v[238:239], v[64:65], 0, v[240:241]
	global_load_lds_dwordx4 v[238:239], off
	s_add_i32 m0, s99, 0x400
	v_lshl_add_u64 v[238:239], v[238:239], 0, s[100:101]
	global_load_lds_dwordx4 v[238:239], off
	s_add_i32 m0, s99, 0x800
	v_lshl_add_u64 v[238:239], v[238:239], 0, s[100:101]
	global_load_lds_dwordx4 v[238:239], off
	s_add_i32 m0, s99, 0xc00
	v_lshl_add_u64 v[238:239], v[238:239], 0, s[100:101]
	global_load_lds_dwordx4 v[238:239], off
	s_waitcnt vmcnt(0)
	ds_read_b128 v[28:31], v242
	ds_read_b128 v[36:39], v242 offset:2048
	ds_read_b128 v[44:47], v242 offset:4096
	ds_read_b128 v[52:55], v242 offset:6144
	ds_read_b128 v[32:35], v243
	ds_read_b128 v[40:43], v243 offset:2048
	ds_read_b128 v[48:51], v243 offset:4096
	ds_read_b128 v[56:59], v243 offset:6144
	ds_read_b128 v[60:63], v244
	ds_read_b128 v[68:71], v244 offset:2048
	ds_read_b128 v[64:67], v245
	ds_read_b128 v[72:75], v245 offset:2048
	s_waitcnt lgkmcnt(0)
	s_nop 0
	s_nop 0
	s_nop 0
	s_nop 0
	s_nop 0
	s_nop 0
	s_nop 0
	s_nop 0
	s_nop 0
	s_nop 0
	s_nop 0
	v_mfma_f32_16x16x32_bf16 v[76:79], v[60:63], v[28:31], 0
	v_mfma_f32_16x16x32_bf16 v[28:31], v[68:71], v[28:31], 0
	v_mfma_f32_16x16x32_bf16 v[80:83], v[60:63], v[36:39], 0
	v_mfma_f32_16x16x32_bf16 v[36:39], v[68:71], v[36:39], 0
	v_mfma_f32_16x16x32_bf16 v[84:87], v[60:63], v[44:47], 0
	v_mfma_f32_16x16x32_bf16 v[44:47], v[68:71], v[44:47], 0
	v_mfma_f32_16x16x32_bf16 v[60:63], v[60:63], v[52:55], 0
	v_mfma_f32_16x16x32_bf16 v[52:55], v[68:71], v[52:55], 0
	v_mfma_f32_16x16x32_bf16 v[68:71], v[64:67], v[32:35], v[76:79]
	v_mfma_f32_16x16x32_bf16 v[28:31], v[72:75], v[32:35], v[28:31]
	v_mfma_f32_16x16x32_bf16 v[32:35], v[64:67], v[40:43], v[80:83]
	v_mfma_f32_16x16x32_bf16 v[36:39], v[72:75], v[40:43], v[36:39]
	v_mfma_f32_16x16x32_bf16 v[40:43], v[64:67], v[48:51], v[84:87]
	v_mfma_f32_16x16x32_bf16 v[44:47], v[72:75], v[48:51], v[44:47]
	v_mfma_f32_16x16x32_bf16 v[48:51], v[64:67], v[56:59], v[60:63]
	v_mfma_f32_16x16x32_bf16 v[52:55], v[72:75], v[56:59], v[52:55]
	ds_write_b128 v27, v[68:71]
	s_nop 0
	ds_write_b128 v27, v[28:31] offset:64
	ds_write_b128 v27, v[32:35] offset:2048
	ds_write_b128 v27, v[36:39] offset:2112
	ds_write_b128 v27, v[40:43] offset:4096
	ds_write_b128 v27, v[44:47] offset:4160
	ds_write_b128 v27, v[48:51] offset:6144
	ds_write_b128 v27, v[52:55] offset:6208
	s_waitcnt lgkmcnt(0)
	s_barrier
; #define LAS __attribute__((address_space(3)))
; __device__ __forceinline__ float bflo(unsigned w) { return __uint_as_float(w << 16); }
; __device__ __forceinline__ float bfhi(unsigned w) { return __uint_as_float(w & 0xffff0000u); }
; __device__ __forceinline__ unsigned pk2(float lo, float hi) { return pg8::cvt_pk_bf16(lo, hi); }
;     __device__ __forceinline__ void apply4(int row, int col, f32x4 v, const Pre& p) const {
;         const u32x2 gw = p.gw; bf16_t* op = O + (size_t)row * DM + col;
;         v = (f32x4){bflo(gw.x) * v[0], bfhi(gw.x) * v[1], bflo(gw.y) * v[2], bfhi(gw.y) * v[3]};
;         if (SECOND) { const u32x2 pw = p.pw; v = v + (f32x4){bflo(pw.x), bfhi(pw.x), bflo(pw.y), bfhi(pw.y)}; }
;         u32x2 w; w.x = pk2(v[0], v[1]); w.y = pk2(v[2], v[3]); *(u32x2*)op = w;
; template <int CT, class Epi> __device__ __forceinline__ void skinny_gemm(LAS unsigned char* lds, const bf16_t* A, const bf16_t* Bt, int N, int K, const Epi& E, int first) {
;     ...
; #pragma unroll
;         for (int e = 0; e < CT / 2; ++e) { const int idx = tid + e * 512, row = idx / (4 * CT), c4 = idx % (4 * CT);
;             f32x4 v = *(const LAS f32x4*)(red + row * (16 * CT) + c4 * 4);
; #pragma unroll
;             for (int w = 1; w < 8; ++w) v = v + *(const LAS f32x4*)(red + w * (64 * 16 * CT) + row * (16 * CT) + c4 * 4);
;             E.apply4(NTOK_P + mt * 64 + row, nt * 16 * CT + c4 * 4, v, pre[e]); }
;         __syncthreads();
	ds_read_b128 v[28:31], v26
	ds_read_b128 v[32:35], v26 offset:8192
	ds_read_b128 v[36:39], v26 offset:16384
	ds_read_b128 v[40:43], v26 offset:24576
	v_add_u32_e32 v44, s8, v25
	v_ashrrev_i32_e32 v45, 31, v44
	s_waitcnt lgkmcnt(2)
	v_pk_add_f32 v[30:31], v[30:31], v[34:35]
	v_pk_add_f32 v[32:33], v[28:29], v[32:33]
	s_waitcnt lgkmcnt(1)
	v_pk_add_f32 v[34:35], v[30:31], v[38:39]
	ds_read_b128 v[28:31], v26 offset:32768
	v_pk_add_f32 v[32:33], v[32:33], v[36:37]
	s_waitcnt lgkmcnt(1)
	v_pk_add_f32 v[36:37], v[34:35], v[42:43]
	v_pk_add_f32 v[40:41], v[32:33], v[40:41]
	ds_read_b128 v[32:35], v26 offset:40960
	s_waitcnt lgkmcnt(1)
	v_pk_add_f32 v[42:43], v[36:37], v[30:31]
	ds_read_b128 v[36:39], v26 offset:49152
	v_pk_add_f32 v[40:41], v[40:41], v[28:29]
	ds_read_b128 v[28:31], v26 offset:57344
	s_waitcnt lgkmcnt(2)
	v_pk_add_f32 v[34:35], v[42:43], v[34:35]
	v_pk_add_f32 v[32:33], v[40:41], v[32:33]
	s_waitcnt lgkmcnt(1)
	v_pk_add_f32 v[34:35], v[34:35], v[38:39]
	v_pk_add_f32 v[32:33], v[32:33], v[36:37]
	v_lshlrev_b32_e32 v46, 16, v92
	v_and_b32_e32 v47, 0xffff0000, v92
	s_waitcnt lgkmcnt(0)
	v_pk_add_f32 v[30:31], v[34:35], v[30:31]
	v_pk_add_f32 v[28:29], v[32:33], v[28:29]
	v_lshlrev_b32_e32 v34, 16, v88
	v_and_b32_e32 v35, 0xffff0000, v88
	s_add_i32 s4, s4, s34
	s_add_i32 s1, s1, s83
	s_add_i32 s0, s0, s82
	v_lshlrev_b32_e32 v48, 16, v93
	v_and_b32_e32 v49, 0xffff0000, v93
	v_lshl_add_u64 v[32:33], v[44:45], 1, v[90:91]
	v_lshlrev_b32_e32 v36, 16, v89
	v_and_b32_e32 v37, 0xffff0000, v89
	v_pk_fma_f32 v[28:29], v[28:29], v[34:35], v[46:47]
	s_cmpk_lt_i32 s4, 0x100
	v_pk_fma_f32 v[30:31], v[30:31], v[36:37], v[48:49]
	v_cvt_pk_bf16_f32 v28, v28, v29
	s_nop 0
	v_cvt_pk_bf16_f32 v29, v30, v31
	global_store_dwordx2 v[32:33], v[28:29], off
	s_barrier
	s_cbranch_scc1 .LBB0_708

; #define LAS __attribute__((address_space(3)))
; __device__ __forceinline__ int opq(int v) { asm volatile("" : "+v"(v)); return v; }
; template <int CT, class Epi> __device__ __forceinline__ void skinny_gemm(LAS unsigned char* lds, const bf16_t* A, const bf16_t* Bt, int N, int K, const Epi& E, int first) {
;     const int tid = opq(threadIdx.x), lane = tid & 63, wave = __builtin_amdgcn_readfirstlane(tid >> 6), r = lane & 15, qd = lane >> 4;
;     const int G = gridDim.x, nunits = 8 * (N / (16 * CT)), kw = K / 8, nsteps = kw / 32;
;     LAS float* red = (LAS float*)lds;
;     for (int u = (int)((blockIdx.x + G - first % G) % G); u < nunits; u += G) {
;         const int mt = u & 7, nt = u >> 3;
;         const bf16_t* ap = A + (size_t)(NTOK_P + mt * 64 + r) * K + wave * kw + 8 * qd;
;         const bf16_t* bp = Bt + (size_t)(nt * 16 * CT + r) * K + wave * kw + 8 * qd;
.LBB0_1029:
	v_mov_b32_e32 v0, v184
	s_and_b64 vcc, exec, s[42:43]
	v_readfirstlane_b32 s0, v0
	s_cbranch_vccnz .LBB0_1040
	s_ashr_i32 s0, s0, 6
	s_lshl_b32 s4, s0, 9
	v_ashrrev_i32_e32 v2, 31, v0
	s_lshl_b32 s0, s0, 13
	s_ashr_i32 s5, s4, 31
	v_lshrrev_b32_e32 v2, 29, v2
	s_add_i32 s0, s0, 0
	v_and_b32_e32 v60, 15, v0
	v_add_u32_e32 v2, v0, v2
	s_cmp_lg_u64 s[16:17], 0
	v_ashrrev_i32_e32 v61, 3, v2
	v_and_b32_e32 v2, -8, v2
	v_lshl_add_u32 v20, v60, 7, s0
	s_cselect_b64 s[0:1], -1, 0
	s_lshl_b64 s[4:5], s[4:5], 1
	v_sub_u32_e32 v62, v0, v2
	s_add_u32 s4, s70, s4
	v_and_b32_e32 v0, 48, v0
	v_lshlrev_b32_e32 v2, 7, v61
	v_lshlrev_b32_e32 v3, 4, v62
	s_addc_u32 s5, s71, s5
	v_readlane_b32 s12, v255, 35
	v_lshlrev_b32_e32 v63, 2, v62
	s_nop 0
	v_add3_u32 v64, 0, v2, v3
	v_or_b32_e32 v65, 0x4000, v60
	v_lshl_add_u64 v[2:3], s[4:5], 0, v[0:1]
	v_add_u32_e32 v66, v20, v0
	v_readlane_b32 s6, v255, 18
	v_readlane_b32 s7, v255, 11
	v_readlane_b32 s8, v255, 17
	v_readlane_b32 s13, v255, 36
	s_branch .LBB0_1033

; template <int CT, class Epi> __device__ __forceinline__ void skinny_gemm(LAS unsigned char* lds, const bf16_t* A, const bf16_t* Bt, int N, int K, const Epi& E, int first) {
;     ...
;         if (nsteps >= 4) {
; #pragma unroll 1
;             for (int s0 = 0; s0 < nsteps; s0 += 4) SKINNY_GROUP(4, s0);
.LBB0_1034:
	s_nop 0
	v_lshl_add_u64 v[68:69], v[58:59], 0, v[0:1]
	s_mov_b32 s5, 0x7b00000
	v_add_co_u32_e32 v120, vcc, s5, v68
	s_mov_b32 s5, 0x7b20000
	s_nop 0
	v_addc_co_u32_e32 v121, vcc, 0, v69, vcc
	v_add_co_u32_e32 v128, vcc, s5, v68
	s_mov_b32 s5, 0x7b40000
	s_nop 0
	v_addc_co_u32_e32 v129, vcc, 0, v69, vcc
	v_add_co_u32_e32 v136, vcc, s5, v68
	s_mov_b32 s5, 0x7b60000
	s_nop 0
	v_addc_co_u32_e32 v137, vcc, 0, v69, vcc
	v_add_co_u32_e32 v144, vcc, s5, v68
	s_mov_b32 s5, 0x1600000
	s_nop 0
	v_addc_co_u32_e32 v145, vcc, 0, v69, vcc
	v_lshl_add_u64 v[68:69], v[58:59], 0, v[56:57]
	v_add_co_u32_e32 v152, vcc, s5, v68
	s_mov_b32 s5, 0x1620000
	s_nop 0
	v_addc_co_u32_e32 v153, vcc, 0, v69, vcc
	v_add_co_u32_e32 v160, vcc, s5, v68
	s_nop 1
	v_addc_co_u32_e32 v161, vcc, 0, v69, vcc
	s_mov_b32 s100, 0x10000
	s_mov_b32 s101, 0
	v_readfirstlane_b32 s98, v184
	v_and_b32_e32 v246, 63, v184
	s_nop 1
	s_lshr_b32 s98, s98, 6
	s_lshl_b32 s99, s98, 12
	s_add_i32 s99, s99, 0x10000
	s_lshl_b32 s98, s98, 13
	v_and_b32_e32 v247, 15, v246
	v_lshrrev_b32_e32 v248, 4, v246
	v_lshrrev_b32_e32 v249, 3, v246
	v_and_b32_e32 v246, 7, v246
	v_xor_b32_e32 v246, v246, v249
	v_sub_u32_e32 v249, v249, v247
	v_sub_u32_e32 v246, v246, v248
	v_lshlrev_b32_e32 v249, 13, v249
	v_lshl_add_u32 v240, v246, 4, v249
	v_ashrrev_i32_e32 v241, 31, v240
	v_and_b32_e32 v246, 7, v247
	v_xor_b32_e32 v246, v246, v248
	v_lshlrev_b32_e32 v246, 4, v246
	v_lshl_add_u32 v246, v247, 7, v246
	v_add_u32_e32 v242, s98, v246
	v_xor_b32_e32 v243, 64, v242
	v_add_u32_e32 v244, s99, v246
	v_xor_b32_e32 v245, 64, v244
	v_add_u32_e32 v246, 0x80, v240
	v_ashrrev_i32_e32 v247, 31, v246
	s_mov_b32 m0, s98
	v_lshl_add_u64 v[236:237], v[120:121], 0, v[240:241]
	global_load_lds_dwordx4 v[236:237], off
	s_add_i32 m0, s98, 0x400
	v_lshl_add_u64 v[236:237], v[236:237], 0, s[100:101]
	global_load_lds_dwordx4 v[236:237], off
	s_add_i32 m0, s98, 0x800
	v_lshl_add_u64 v[236:237], v[236:237], 0, s[100:101]
	global_load_lds_dwordx4 v[236:237], off
	s_add_i32 m0, s98, 0xc00
	v_lshl_add_u64 v[236:237], v[236:237], 0, s[100:101]
	global_load_lds_dwordx4 v[236:237], off
	s_add_i32 m0, s98, 0x1000
	v_lshl_add_u64 v[236:237], v[236:237], 0, s[100:101]
	global_load_lds_dwordx4 v[236:237], off
	s_add_i32 m0, s98, 0x1400
	v_lshl_add_u64 v[236:237], v[236:237], 0, s[100:101]
	global_load_lds_dwordx4 v[236:237], off
	s_add_i32 m0, s98, 0x1800
	v_lshl_add_u64 v[236:237], v[236:237], 0, s[100:101]
	global_load_lds_dwordx4 v[236:237], off
	s_add_i32 m0, s98, 0x1c00
	v_lshl_add_u64 v[236:237], v[236:237], 0, s[100:101]
	global_load_lds_dwordx4 v[236:237], off
	s_mov_b32 m0, s99
	v_lshl_add_u64 v[238:239], v[152:153], 0, v[240:241]
	global_load_lds_dwordx4 v[238:239], off
	s_add_i32 m0, s99, 0x400
	v_lshl_add_u64 v[238:239], v[238:239], 0, s[100:101]
	global_load_lds_dwordx4 v[238:239], off
	s_add_i32 m0, s99, 0x800
	v_lshl_add_u64 v[238:239], v[238:239], 0, s[100:101]
	global_load_lds_dwordx4 v[238:239], off
	s_add_i32 m0, s99, 0xc00
	v_lshl_add_u64 v[238:239], v[238:239], 0, s[100:101]
	global_load_lds_dwordx4 v[238:239], off
	s_waitcnt vmcnt(0)
	ds_read_b128 v[68:71], v242
	ds_read_b128 v[76:79], v242 offset:2048
	ds_read_b128 v[84:87], v242 offset:4096
	ds_read_b128 v[92:95], v242 offset:6144
	ds_read_b128 v[72:75], v243
	ds_read_b128 v[80:83], v243 offset:2048
	ds_read_b128 v[88:91], v243 offset:4096
	ds_read_b128 v[96:99], v243 offset:6144
	ds_read_b128 v[100:103], v244
	ds_read_b128 v[108:111], v244 offset:2048
	ds_read_b128 v[104:107], v245
	ds_read_b128 v[112:115], v245 offset:2048
	s_waitcnt lgkmcnt(0)
	s_mov_b32 m0, s98
	v_lshl_add_u64 v[236:237], v[120:121], 0, v[246:247]
	global_load_lds_dwordx4 v[236:237], off
	s_add_i32 m0, s98, 0x400
	v_lshl_add_u64 v[236:237], v[236:237], 0, s[100:101]
	global_load_lds_dwordx4 v[236:237], off
	s_add_i32 m0, s98, 0x800
	v_lshl_add_u64 v[236:237], v[236:237], 0, s[100:101]
	global_load_lds_dwordx4 v[236:237], off
	s_add_i32 m0, s98, 0xc00
	v_lshl_add_u64 v[236:237], v[236:237], 0, s[100:101]
	global_load_lds_dwordx4 v[236:237], off
	s_add_i32 m0, s98, 0x1000
	v_lshl_add_u64 v[236:237], v[236:237], 0, s[100:101]
	global_load_lds_dwordx4 v[236:237], off
	s_add_i32 m0, s98, 0x1400
	v_lshl_add_u64 v[236:237], v[236:237], 0, s[100:101]
	global_load_lds_dwordx4 v[236:237], off
	s_add_i32 m0, s98, 0x1800
	v_lshl_add_u64 v[236:237], v[236:237], 0, s[100:101]
	global_load_lds_dwordx4 v[236:237], off
	s_add_i32 m0, s98, 0x1c00
	v_lshl_add_u64 v[236:237], v[236:237], 0, s[100:101]
	global_load_lds_dwordx4 v[236:237], off
	s_mov_b32 m0, s99
	v_lshl_add_u64 v[238:239], v[152:153], 0, v[246:247]
	global_load_lds_dwordx4 v[238:239], off
	s_add_i32 m0, s99, 0x400
	v_lshl_add_u64 v[238:239], v[238:239], 0, s[100:101]
	global_load_lds_dwordx4 v[238:239], off
	s_add_i32 m0, s99, 0x800
	v_lshl_add_u64 v[238:239], v[238:239], 0, s[100:101]
	global_load_lds_dwordx4 v[238:239], off
	s_add_i32 m0, s99, 0xc00
	v_lshl_add_u64 v[238:239], v[238:239], 0, s[100:101]
	global_load_lds_dwordx4 v[238:239], off
	s_nop 0
	s_nop 0
	s_nop 0
	s_nop 0
	s_nop 0
	s_nop 0
	s_nop 0
	s_nop 0
	s_nop 0
	s_nop 0
	s_nop 0
	v_mfma_f32_16x16x32_bf16 v[20:23], v[100:103], v[68:71], v[20:23]
	v_mfma_f32_16x16x32_bf16 v[24:27], v[108:111], v[68:71], v[24:27]
	v_mfma_f32_16x16x32_bf16 v[28:31], v[100:103], v[76:79], v[28:31]
	v_mfma_f32_16x16x32_bf16 v[32:35], v[108:111], v[76:79], v[32:35]
	v_mfma_f32_16x16x32_bf16 v[36:39], v[100:103], v[84:87], v[36:39]
	v_mfma_f32_16x16x32_bf16 v[40:43], v[108:111], v[84:87], v[40:43]
	v_mfma_f32_16x16x32_bf16 v[44:47], v[100:103], v[92:95], v[44:47]
	v_mfma_f32_16x16x32_bf16 v[48:51], v[108:111], v[92:95], v[48:51]
	v_mfma_f32_16x16x32_bf16 v[20:23], v[104:107], v[72:75], v[20:23]
	v_mfma_f32_16x16x32_bf16 v[24:27], v[112:115], v[72:75], v[24:27]
	v_mfma_f32_16x16x32_bf16 v[28:31], v[104:107], v[80:83], v[28:31]
	v_mfma_f32_16x16x32_bf16 v[32:35], v[112:115], v[80:83], v[32:35]
	v_mfma_f32_16x16x32_bf16 v[36:39], v[104:107], v[88:91], v[36:39]
	v_mfma_f32_16x16x32_bf16 v[40:43], v[112:115], v[88:91], v[40:43]
	v_mfma_f32_16x16x32_bf16 v[44:47], v[104:107], v[96:99], v[44:47]
	v_mfma_f32_16x16x32_bf16 v[48:51], v[112:115], v[96:99], v[48:51]
	s_waitcnt vmcnt(0)
; #define LAS __attribute__((address_space(3)))
; __device__ __forceinline__ float bflo(unsigned w) { return __uint_as_float(w << 16); }
; __device__ __forceinline__ float bfhi(unsigned w) { return __uint_as_float(w & 0xffff0000u); }
;     __device__ __forceinline__ void apply4(int row, int col, f32x4 v, const Pre& p) const {
;         const size_t off = (size_t)row * DM + col; const u32x2 bw = p.bw;
;         v = v + (f32x4){bflo(bw.x), bfhi(bw.x), bflo(bw.y), bfhi(bw.y)};
;         if (Xf) *(f32x4*)(Xf + off) = v;
; template <int CT, class Epi> __device__ __forceinline__ void skinny_gemm(LAS unsigned char* lds, const bf16_t* A, const bf16_t* Bt, int N, int K, const Epi& E, int first) {
;     ...
;         if (nsteps >= 4) {
; #pragma unroll 1
;             for (int s0 = 0; s0 < nsteps; s0 += 4) SKINNY_GROUP(4, s0);
;         } else SKINNY_GROUP(2, 0);
;     ...
; #pragma unroll
;         for (int rt = 0; rt < 4; ++rt)
; #pragma unroll
;             for (int ct = 0; ct < CT; ++ct) *(LAS f32x4*)(red + wave * (64 * 16 * CT) + (rt * 16 + r) * (16 * CT) + ct * 16 + 4 * qd) = acc[rt][ct];
;         __syncthreads();
; #pragma unroll
;         for (int e = 0; e < CT / 2; ++e) { const int idx = tid + e * 512, row = idx / (4 * CT), c4 = idx % (4 * CT);
;             f32x4 v = *(const LAS f32x4*)(red + row * (16 * CT) + c4 * 4);
; #pragma unroll
;             for (int w = 1; w < 8; ++w) v = v + *(const LAS f32x4*)(red + w * (64 * 16 * CT) + row * (16 * CT) + c4 * 4);
;             E.apply4(NTOK_P + mt * 64 + row, nt * 16 * CT + c4 * 4, v, pre[e]); }
	ds_read_b128 v[116:119], v242
	ds_read_b128 v[124:127], v242 offset:2048
	ds_read_b128 v[132:135], v242 offset:4096
	ds_read_b128 v[140:143], v242 offset:6144
	ds_read_b128 v[120:123], v243
	ds_read_b128 v[128:131], v243 offset:2048
	ds_read_b128 v[136:139], v243 offset:4096
	ds_read_b128 v[144:147], v243 offset:6144
	ds_read_b128 v[148:151], v244
	ds_read_b128 v[156:159], v244 offset:2048
	ds_read_b128 v[152:155], v245
	ds_read_b128 v[160:163], v245 offset:2048
	s_waitcnt lgkmcnt(0)
	v_mfma_f32_16x16x32_bf16 v[20:23], v[148:151], v[116:119], v[20:23]
	v_mfma_f32_16x16x32_bf16 v[24:27], v[156:159], v[116:119], v[24:27]
	v_mfma_f32_16x16x32_bf16 v[28:31], v[148:151], v[124:127], v[28:31]
	v_mfma_f32_16x16x32_bf16 v[32:35], v[156:159], v[124:127], v[32:35]
	v_mfma_f32_16x16x32_bf16 v[36:39], v[148:151], v[132:135], v[36:39]
	v_mfma_f32_16x16x32_bf16 v[40:43], v[156:159], v[132:135], v[40:43]
	v_mfma_f32_16x16x32_bf16 v[44:47], v[148:151], v[140:143], v[44:47]
	v_mfma_f32_16x16x32_bf16 v[48:51], v[156:159], v[140:143], v[48:51]
	v_mfma_f32_16x16x32_bf16 v[20:23], v[152:155], v[120:123], v[20:23]
	v_mfma_f32_16x16x32_bf16 v[24:27], v[160:163], v[120:123], v[24:27]
	v_mfma_f32_16x16x32_bf16 v[28:31], v[152:155], v[128:131], v[28:31]
	v_mfma_f32_16x16x32_bf16 v[32:35], v[160:163], v[128:131], v[32:35]
	v_mfma_f32_16x16x32_bf16 v[36:39], v[152:155], v[136:139], v[36:39]
	v_mfma_f32_16x16x32_bf16 v[40:43], v[160:163], v[136:139], v[40:43]
	v_mfma_f32_16x16x32_bf16 v[44:47], v[152:155], v[144:147], v[44:47]
	v_mfma_f32_16x16x32_bf16 v[48:51], v[160:163], v[144:147], v[48:51]
	s_add_i32 s4, s4, 4
	s_mov_b64 s[10:11], 0x100
	s_cmp_gt_u32 s4, 11
	v_lshl_add_u64 v[58:59], v[58:59], 0, s[10:11]
	s_cbranch_scc0 .LBB0_1034
	ds_write_b128 v66, v[20:23]
	ds_write_b128 v66, v[24:27] offset:64
	ds_write_b128 v66, v[28:31] offset:2048
	ds_write_b128 v66, v[32:35] offset:2112
	ds_write_b128 v66, v[36:39] offset:4096
	ds_write_b128 v66, v[40:43] offset:4160
	ds_write_b128 v66, v[44:47] offset:6144
	ds_write_b128 v66, v[48:51] offset:6208
	s_waitcnt lgkmcnt(0)
	s_barrier
	ds_read_b128 v[20:23], v64
	ds_read_b128 v[24:27], v64 offset:8192
	ds_read_b128 v[28:31], v64 offset:16384
	ds_read_b128 v[32:35], v64 offset:24576
	s_lshl_b32 s4, s8, 2
	s_andn2_b32 s4, s4, 31
	s_waitcnt lgkmcnt(2)
	v_pk_add_f32 v[22:23], v[22:23], v[26:27]
	v_pk_add_f32 v[24:25], v[20:21], v[24:25]
	s_waitcnt lgkmcnt(1)
	v_pk_add_f32 v[26:27], v[22:23], v[30:31]
	ds_read_b128 v[20:23], v64 offset:32768
	v_pk_add_f32 v[24:25], v[24:25], v[28:29]
	s_waitcnt lgkmcnt(1)
	v_pk_add_f32 v[28:29], v[26:27], v[34:35]
	v_pk_add_f32 v[32:33], v[24:25], v[32:33]
	ds_read_b128 v[24:27], v64 offset:40960
	s_waitcnt lgkmcnt(1)
	v_pk_add_f32 v[34:35], v[28:29], v[22:23]
	ds_read_b128 v[28:31], v64 offset:49152
	v_pk_add_f32 v[32:33], v[32:33], v[20:21]
	ds_read_b128 v[20:23], v64 offset:57344
	s_waitcnt lgkmcnt(2)
	v_pk_add_f32 v[26:27], v[34:35], v[26:27]
	v_pk_add_f32 v[24:25], v[32:33], v[24:25]
	v_add_u32_e32 v36, s4, v63
	s_waitcnt lgkmcnt(1)
	v_pk_add_f32 v[26:27], v[26:27], v[30:31]
	v_pk_add_f32 v[24:25], v[24:25], v[28:29]
	v_ashrrev_i32_e32 v37, 31, v36
	v_lshlrev_b32_e32 v38, 16, v54
	v_and_b32_e32 v39, 0xffff0000, v54
	v_lshlrev_b32_e32 v40, 16, v55
	v_and_b32_e32 v41, 0xffff0000, v55
	s_waitcnt lgkmcnt(0)
	v_pk_add_f32 v[22:23], v[26:27], v[22:23]
	v_pk_add_f32 v[20:21], v[24:25], v[20:21]
	v_lshlrev_b64 v[24:25], 10, v[52:53]
	v_lshl_add_u64 v[24:25], v[24:25], 0, v[36:37]
	v_pk_add_f32 v[22:23], v[22:23], v[40:41]
	v_pk_add_f32 v[20:21], v[20:21], v[38:39]
	s_and_b64 vcc, exec, s[0:1]
	s_cbranch_vccz .LBB0_1037
	v_lshl_add_u64 v[26:27], v[24:25], 2, s[68:69]
	global_store_dwordx4 v[26:27], v[20:23], off
